# Toeplitz k-loops: tap addresses advanced incrementally, range test on the linear address (30 -> 15 VALU per iteration)
# baseline (speedup 1.0000x reference)
.LBB0_563:
	s_ashr_i32 s0, s2, 1
	s_max_i32 s26, s0, 0
	s_and_b64 s[0:1], s[38:39], exec
	s_cselect_b32 s0, 0, s26
	s_add_i32 s1, s2, 12
	s_ashr_i32 s1, s1, 1
	s_min_i32 s1, s1, 15
	s_and_b64 s[26:27], s[38:39], exec
	s_cselect_b32 s33, s1, 15
	s_cmp_gt_i32 s0, s33
	s_cbranch_scc1 .LBB0_581
	v_lshrrev_b32_e32 v2, 1, v95
	s_lshl_b32 s1, s0, 1
	s_add_i32 s36, s0, -1
	v_or_b32_e32 v0, s1, v2
	s_lshl_b32 s0, s0, 6
	v_sub_u32_e32 v0, v0, v88
	v_sub_u32_e32 v2, v88, v2
	v_add3_u32 v3, v92, s0, v94
	s_add_i32 s0, 0, 0x9000
	v_mov_b32_e32 v4, 0
	v_add_u32_e32 v0, -12, v0
	v_subrev_u32_e32 v2, s1, v2
	v_add3_u32 v3, v3, v93, s0
	v_mov_b32_e32 v5, v4
	v_mov_b32_e32 v6, v4
	v_mov_b32_e32 v7, v4
	v_mov_b32_e32 v8, v4
	v_mov_b32_e32 v9, v4
	v_mov_b32_e32 v10, v4
	v_mov_b32_e32 v11, v4
	v_mov_b32_e32 v12, v4
	v_mov_b32_e32 v13, v4
	v_mov_b32_e32 v14, v4
	v_mov_b32_e32 v15, v4
	v_mov_b32_e32 v16, v4
	v_mov_b32_e32 v17, v4
	v_mov_b32_e32 v18, v4
	v_mov_b32_e32 v19, v4
	v_add_u32_e32 v234, 12, v0
	v_cndmask_b32_e64 v230, v234, v2, s[38:39]
	v_max_i32_e32 v242, 0, v230
	v_lshl_add_u32 v242, v242, 9, v91
	v_add_u32_e32 v235, 8, v0
	v_add_u32_e32 v239, 4, v2
	v_cndmask_b32_e64 v231, v235, v239, s[38:39]
	v_max_i32_e32 v243, 0, v231
	v_lshl_add_u32 v243, v243, 9, v91
	v_add_u32_e32 v236, 4, v0
	v_add_u32_e32 v240, 8, v2
	v_cndmask_b32_e64 v232, v236, v240, s[38:39]
	v_max_i32_e32 v244, 0, v232
	v_lshl_add_u32 v244, v244, 9, v91
	v_add_u32_e32 v241, 12, v2
	v_cndmask_b32_e64 v233, v0, v241, s[38:39]
	v_max_i32_e32 v245, 0, v233
	v_lshl_add_u32 v245, v245, 9, v91
	v_cmp_lt_i32_e64 s[98:99], -1, v230
	v_cmp_lt_i32_e64 s[100:101], -1, v231
	v_cmp_lt_i32_e64 vcc, -1, v232
	v_cndmask_b32_e64 v242, v246, v242, s[98:99]
	v_cmp_lt_i32_e64 s[98:99], -1, v233
	v_cndmask_b32_e64 v243, v246, v243, s[100:101]
	v_cndmask_b32_e64 v244, v246, v244, vcc
	s_nop 0
	v_cndmask_b32_e64 v245, v246, v245, s[98:99]
	v_lshl_add_u32 v234, v230, 9, v91
	v_lshl_add_u32 v235, v231, 9, v91
	v_lshl_add_u32 v236, v232, 9, v91
	v_lshl_add_u32 v237, v233, 9, v91
	v_mov_b32_e32 v238, 0x400
	v_mov_b32_e32 v239, 0xfffffc00
	v_cndmask_b32_e64 v238, v238, v239, s[38:39]
.LBB0_565:
	ds_read_b128 v[214:217], v242 offset:4096
	ds_read_b128 v[218:221], v243 offset:4096
	ds_read_b128 v[222:225], v244 offset:4096
	ds_read_b128 v[226:229], v245 offset:4096
	ds_read_b128 v[20:23], v3
	v_add_u32_e32 v0, 2, v0
	v_add_u32_e32 v2, -2, v2
	v_add_u32_e32 v3, 64, v3
	v_add_u32_e32 v234, v238, v234
	v_add_u32_e32 v235, v238, v235
	v_add_u32_e32 v236, v238, v236
	v_add_u32_e32 v237, v238, v237
	v_cmp_lt_i32_e64 s[98:99], v234, v91
	v_cmp_lt_i32_e64 s[100:101], v235, v91
	v_cmp_lt_i32_e64 vcc, v236, v91
	v_cndmask_b32_e64 v242, v234, v246, s[98:99]
	v_cmp_lt_i32_e64 s[98:99], v237, v91
	v_cndmask_b32_e64 v243, v235, v246, s[100:101]
	v_cndmask_b32_e64 v244, v236, v246, vcc
	s_nop 0
	v_cndmask_b32_e64 v245, v237, v246, s[98:99]
	s_add_i32 s36, s36, 1
	s_cmp_lt_i32 s36, s33
	s_waitcnt lgkmcnt(0)
	v_mfma_f32_16x16x32_bf16 v[16:19], v[214:217], v[20:23], v[16:19]
	v_mfma_f32_16x16x32_bf16 v[12:15], v[218:221], v[20:23], v[12:15]
	v_mfma_f32_16x16x32_bf16 v[8:11], v[222:225], v[20:23], v[8:11]
	v_mfma_f32_16x16x32_bf16 v[4:7], v[226:229], v[20:23], v[4:7]
	s_cbranch_scc1 .LBB0_565
	s_cmp_eq_u32 s3, 1
	s_cselect_b64 s[44:45], -1, 0
	s_cmp_lg_u32 s3, 1
	s_cbranch_scc1 .LBB0_582
.LBB0_567:
	s_add_i32 s0, s2, 16
	s_ashr_i32 s0, s0, 1
	s_max_i32 s26, s0, 0
	s_and_b64 s[0:1], s[38:39], exec
	s_cselect_b32 s0, 0, s26
	s_add_i32 s1, s2, 28
	s_ashr_i32 s1, s1, 1
	s_min_i32 s1, s1, 15
	s_and_b64 s[26:27], s[38:39], exec
	s_cselect_b32 s33, s1, 15
	s_cmp_gt_i32 s0, s33
	s_cbranch_scc1 .LBB0_570
	v_lshrrev_b32_e32 v2, 1, v95
	s_lshl_b32 s1, s0, 1
	s_add_i32 s36, s0, -1
	v_or_b32_e32 v0, s1, v2
	v_sub_u32_e32 v2, v88, v2
	s_lshl_b32 s0, s0, 6
	v_sub_u32_e32 v0, v0, v88
	v_subrev_u32_e32 v2, s1, v2
	v_add3_u32 v3, v92, s0, v94
	s_add_i32 s0, 0, 0x9000
	v_mov_b32_e32 v20, 0
	v_subrev_u32_e32 v0, 28, v0
	v_add_u32_e32 v2, 28, v2
	v_add3_u32 v3, v3, v93, s0
	v_mov_b32_e32 v21, v20
	v_mov_b32_e32 v22, v20
	v_mov_b32_e32 v23, v20
	v_mov_b32_e32 v24, v20
	v_mov_b32_e32 v25, v20
	v_mov_b32_e32 v26, v20
	v_mov_b32_e32 v27, v20
	v_mov_b32_e32 v28, v20
	v_mov_b32_e32 v29, v20
	v_mov_b32_e32 v30, v20
	v_mov_b32_e32 v31, v20
	v_mov_b32_e32 v32, v20
	v_mov_b32_e32 v33, v20
	v_mov_b32_e32 v34, v20
	v_mov_b32_e32 v35, v20
	v_add_u32_e32 v234, 12, v0
	v_add_u32_e32 v238, -12, v2
	v_cndmask_b32_e64 v230, v234, v238, s[38:39]
	v_max_i32_e32 v242, 0, v230
	v_lshl_add_u32 v242, v242, 9, v91
	v_add_u32_e32 v235, 8, v0
	v_add_u32_e32 v239, -8, v2
	v_cndmask_b32_e64 v231, v235, v239, s[38:39]
	v_max_i32_e32 v243, 0, v231
	v_lshl_add_u32 v243, v243, 9, v91
	v_add_u32_e32 v236, 4, v0
	v_add_u32_e32 v240, -4, v2
	v_cndmask_b32_e64 v232, v236, v240, s[38:39]
	v_max_i32_e32 v244, 0, v232
	v_lshl_add_u32 v244, v244, 9, v91
	v_cndmask_b32_e64 v233, v0, v2, s[38:39]
	v_max_i32_e32 v245, 0, v233
	v_lshl_add_u32 v245, v245, 9, v91
	v_cmp_lt_i32_e64 s[98:99], -1, v230
	v_cmp_lt_i32_e64 s[100:101], -1, v231
	v_cmp_lt_i32_e64 vcc, -1, v232
	v_cndmask_b32_e64 v242, v246, v242, s[98:99]
	v_cmp_lt_i32_e64 s[98:99], -1, v233
	v_cndmask_b32_e64 v243, v246, v243, s[100:101]
	v_cndmask_b32_e64 v244, v246, v244, vcc
	s_nop 0
	v_cndmask_b32_e64 v245, v246, v245, s[98:99]
	v_lshl_add_u32 v234, v230, 9, v91
	v_lshl_add_u32 v235, v231, 9, v91
	v_lshl_add_u32 v236, v232, 9, v91
	v_lshl_add_u32 v237, v233, 9, v91
	v_mov_b32_e32 v238, 0x400
	v_mov_b32_e32 v239, 0xfffffc00
	v_cndmask_b32_e64 v238, v238, v239, s[38:39]
.LBB0_569:
	ds_read_b128 v[214:217], v242 offset:4096
	ds_read_b128 v[218:221], v243 offset:4096
	ds_read_b128 v[222:225], v244 offset:4096
	ds_read_b128 v[226:229], v245 offset:4096
	ds_read_b128 v[36:39], v3
	v_add_u32_e32 v0, 2, v0
	v_add_u32_e32 v2, -2, v2
	v_add_u32_e32 v3, 64, v3
	v_add_u32_e32 v234, v238, v234
	v_add_u32_e32 v235, v238, v235
	v_add_u32_e32 v236, v238, v236
	v_add_u32_e32 v237, v238, v237
	v_cmp_lt_i32_e64 s[98:99], v234, v91
	v_cmp_lt_i32_e64 s[100:101], v235, v91
	v_cmp_lt_i32_e64 vcc, v236, v91
	v_cndmask_b32_e64 v242, v234, v246, s[98:99]
	v_cmp_lt_i32_e64 s[98:99], v237, v91
	v_cndmask_b32_e64 v243, v235, v246, s[100:101]
	v_cndmask_b32_e64 v244, v236, v246, vcc
	s_nop 0
	v_cndmask_b32_e64 v245, v237, v246, s[98:99]
	s_add_i32 s36, s36, 1
	s_cmp_lt_i32 s36, s33
	s_waitcnt lgkmcnt(0)
	v_mfma_f32_16x16x32_bf16 v[32:35], v[214:217], v[36:39], v[32:35]
	v_mfma_f32_16x16x32_bf16 v[28:31], v[218:221], v[36:39], v[28:31]
	v_mfma_f32_16x16x32_bf16 v[24:27], v[222:225], v[36:39], v[24:27]
	v_mfma_f32_16x16x32_bf16 v[20:23], v[226:229], v[36:39], v[20:23]
	s_cbranch_scc1 .LBB0_569
	s_branch .LBB0_571

.LBB0_572:
	s_add_i32 s0, s2, 32
	s_ashr_i32 s0, s0, 1
	s_max_i32 s26, s0, 0
	s_and_b64 s[0:1], s[38:39], exec
	s_cselect_b32 s0, 0, s26
	s_add_i32 s1, s2, 44
	s_ashr_i32 s1, s1, 1
	s_min_i32 s1, s1, 15
	s_and_b64 s[26:27], s[38:39], exec
	s_cselect_b32 s33, s1, 15
	s_cmp_gt_i32 s0, s33
	s_cbranch_scc1 .LBB0_575
	v_lshrrev_b32_e32 v2, 1, v95
	s_lshl_b32 s1, s0, 1
	s_add_i32 s36, s0, -1
	v_or_b32_e32 v0, s1, v2
	v_sub_u32_e32 v2, v88, v2
	s_lshl_b32 s0, s0, 6
	v_sub_u32_e32 v0, v0, v88
	v_subrev_u32_e32 v2, s1, v2
	v_add3_u32 v3, v92, s0, v94
	s_add_i32 s0, 0, 0x9000
	v_mov_b32_e32 v36, 0
	v_subrev_u32_e32 v0, 44, v0
	v_add_u32_e32 v2, 44, v2
	v_add3_u32 v3, v3, v93, s0
	v_mov_b32_e32 v37, v36
	v_mov_b32_e32 v38, v36
	v_mov_b32_e32 v39, v36
	v_mov_b32_e32 v44, v36
	v_mov_b32_e32 v45, v36
	v_mov_b32_e32 v46, v36
	v_mov_b32_e32 v47, v36
	v_mov_b32_e32 v52, v36
	v_mov_b32_e32 v53, v36
	v_mov_b32_e32 v54, v36
	v_mov_b32_e32 v55, v36
	v_mov_b32_e32 v56, v36
	v_mov_b32_e32 v57, v36
	v_mov_b32_e32 v58, v36
	v_mov_b32_e32 v59, v36
	v_add_u32_e32 v234, 12, v0
	v_add_u32_e32 v238, -12, v2
	v_cndmask_b32_e64 v230, v234, v238, s[38:39]
	v_max_i32_e32 v242, 0, v230
	v_lshl_add_u32 v242, v242, 9, v91
	v_add_u32_e32 v235, 8, v0
	v_add_u32_e32 v239, -8, v2
	v_cndmask_b32_e64 v231, v235, v239, s[38:39]
	v_max_i32_e32 v243, 0, v231
	v_lshl_add_u32 v243, v243, 9, v91
	v_add_u32_e32 v236, 4, v0
	v_add_u32_e32 v240, -4, v2
	v_cndmask_b32_e64 v232, v236, v240, s[38:39]
	v_max_i32_e32 v244, 0, v232
	v_lshl_add_u32 v244, v244, 9, v91
	v_cndmask_b32_e64 v233, v0, v2, s[38:39]
	v_max_i32_e32 v245, 0, v233
	v_lshl_add_u32 v245, v245, 9, v91
	v_cmp_lt_i32_e64 s[98:99], -1, v230
	v_cmp_lt_i32_e64 s[100:101], -1, v231
	v_cmp_lt_i32_e64 vcc, -1, v232
	v_cndmask_b32_e64 v242, v246, v242, s[98:99]
	v_cmp_lt_i32_e64 s[98:99], -1, v233
	v_cndmask_b32_e64 v243, v246, v243, s[100:101]
	v_cndmask_b32_e64 v244, v246, v244, vcc
	s_nop 0
	v_cndmask_b32_e64 v245, v246, v245, s[98:99]
	v_lshl_add_u32 v234, v230, 9, v91
	v_lshl_add_u32 v235, v231, 9, v91
	v_lshl_add_u32 v236, v232, 9, v91
	v_lshl_add_u32 v237, v233, 9, v91
	v_mov_b32_e32 v238, 0x400
	v_mov_b32_e32 v239, 0xfffffc00
	v_cndmask_b32_e64 v238, v238, v239, s[38:39]
.LBB0_574:
	ds_read_b128 v[214:217], v242 offset:4096
	ds_read_b128 v[218:221], v243 offset:4096
	ds_read_b128 v[222:225], v244 offset:4096
	ds_read_b128 v[226:229], v245 offset:4096
	ds_read_b128 v[68:71], v3
	v_add_u32_e32 v0, 2, v0
	v_add_u32_e32 v2, -2, v2
	v_add_u32_e32 v3, 64, v3
	v_add_u32_e32 v234, v238, v234
	v_add_u32_e32 v235, v238, v235
	v_add_u32_e32 v236, v238, v236
	v_add_u32_e32 v237, v238, v237
	v_cmp_lt_i32_e64 s[98:99], v234, v91
	v_cmp_lt_i32_e64 s[100:101], v235, v91
	v_cmp_lt_i32_e64 vcc, v236, v91
	v_cndmask_b32_e64 v242, v234, v246, s[98:99]
	v_cmp_lt_i32_e64 s[98:99], v237, v91
	v_cndmask_b32_e64 v243, v235, v246, s[100:101]
	v_cndmask_b32_e64 v244, v236, v246, vcc
	s_nop 0
	v_cndmask_b32_e64 v245, v237, v246, s[98:99]
	s_add_i32 s36, s36, 1
	s_cmp_lt_i32 s36, s33
	s_waitcnt lgkmcnt(0)
	v_mfma_f32_16x16x32_bf16 v[56:59], v[214:217], v[68:71], v[56:59]
	v_mfma_f32_16x16x32_bf16 v[52:55], v[218:221], v[68:71], v[52:55]
	v_mfma_f32_16x16x32_bf16 v[44:47], v[222:225], v[68:71], v[44:47]
	v_mfma_f32_16x16x32_bf16 v[36:39], v[226:229], v[68:71], v[36:39]
	s_cbranch_scc1 .LBB0_574
	s_branch .LBB0_576

.LBB0_577:
	s_add_i32 s0, s2, 48
	s_ashr_i32 s0, s0, 1
	s_max_i32 s3, s0, 0
	s_and_b64 s[0:1], s[38:39], exec
	s_cselect_b32 s0, 0, s3
	s_add_i32 s1, s2, 60
	s_ashr_i32 s1, s1, 1
	s_min_i32 s1, s1, 15
	s_and_b64 s[26:27], s[38:39], exec
	s_cselect_b32 s3, s1, 15
	s_cmp_gt_i32 s0, s3
	s_cbranch_scc1 .LBB0_580
	v_lshrrev_b32_e32 v2, 1, v95
	s_lshl_b32 s1, s0, 1
	s_add_i32 s33, s0, -1
	v_or_b32_e32 v0, s1, v2
	v_sub_u32_e32 v2, v88, v2
	s_lshl_b32 s0, s0, 6
	v_sub_u32_e32 v0, v0, v88
	v_subrev_u32_e32 v2, s1, v2
	v_add3_u32 v3, v92, s0, v94
	s_add_i32 s0, 0, 0x9000
	v_mov_b32_e32 v68, 0
	v_subrev_u32_e32 v0, 60, v0
	v_add_u32_e32 v2, 60, v2
	v_add3_u32 v3, v3, v93, s0
	v_mov_b32_e32 v69, v68
	v_mov_b32_e32 v70, v68
	v_mov_b32_e32 v71, v68
	v_mov_b32_e32 v72, v68
	v_mov_b32_e32 v73, v68
	v_mov_b32_e32 v74, v68
	v_mov_b32_e32 v75, v68
	v_mov_b32_e32 v76, v68
	v_mov_b32_e32 v77, v68
	v_mov_b32_e32 v78, v68
	v_mov_b32_e32 v79, v68
	v_mov_b32_e32 v80, v68
	v_mov_b32_e32 v81, v68
	v_mov_b32_e32 v82, v68
	v_mov_b32_e32 v83, v68
	v_add_u32_e32 v234, 12, v0
	v_add_u32_e32 v238, -12, v2
	v_cndmask_b32_e64 v230, v234, v238, s[38:39]
	v_max_i32_e32 v242, 0, v230
	v_lshl_add_u32 v242, v242, 9, v91
	v_add_u32_e32 v235, 8, v0
	v_add_u32_e32 v239, -8, v2
	v_cndmask_b32_e64 v231, v235, v239, s[38:39]
	v_max_i32_e32 v243, 0, v231
	v_lshl_add_u32 v243, v243, 9, v91
	v_add_u32_e32 v236, 4, v0
	v_add_u32_e32 v240, -4, v2
	v_cndmask_b32_e64 v232, v236, v240, s[38:39]
	v_max_i32_e32 v244, 0, v232
	v_lshl_add_u32 v244, v244, 9, v91
	v_cndmask_b32_e64 v233, v0, v2, s[38:39]
	v_max_i32_e32 v245, 0, v233
	v_lshl_add_u32 v245, v245, 9, v91
	v_cmp_lt_i32_e64 s[98:99], -1, v230
	v_cmp_lt_i32_e64 s[100:101], -1, v231
	v_cmp_lt_i32_e64 vcc, -1, v232
	v_cndmask_b32_e64 v242, v246, v242, s[98:99]
	v_cmp_lt_i32_e64 s[98:99], -1, v233
	v_cndmask_b32_e64 v243, v246, v243, s[100:101]
	v_cndmask_b32_e64 v244, v246, v244, vcc
	s_nop 0
	v_cndmask_b32_e64 v245, v246, v245, s[98:99]
	v_lshl_add_u32 v234, v230, 9, v91
	v_lshl_add_u32 v235, v231, 9, v91
	v_lshl_add_u32 v236, v232, 9, v91
	v_lshl_add_u32 v237, v233, 9, v91
	v_mov_b32_e32 v238, 0x400
	v_mov_b32_e32 v239, 0xfffffc00
	v_cndmask_b32_e64 v238, v238, v239, s[38:39]
.LBB0_579:
	ds_read_b128 v[214:217], v242 offset:4096
	ds_read_b128 v[218:221], v243 offset:4096
	ds_read_b128 v[222:225], v244 offset:4096
	ds_read_b128 v[226:229], v245 offset:4096
	ds_read_b128 v[84:87], v3
	v_add_u32_e32 v0, 2, v0
	v_add_u32_e32 v2, -2, v2
	v_add_u32_e32 v3, 64, v3
	v_add_u32_e32 v234, v238, v234
	v_add_u32_e32 v235, v238, v235
	v_add_u32_e32 v236, v238, v236
	v_add_u32_e32 v237, v238, v237
	v_cmp_lt_i32_e64 s[98:99], v234, v91
	v_cmp_lt_i32_e64 s[100:101], v235, v91
	v_cmp_lt_i32_e64 vcc, v236, v91
	v_cndmask_b32_e64 v242, v234, v246, s[98:99]
	v_cmp_lt_i32_e64 s[98:99], v237, v91
	v_cndmask_b32_e64 v243, v235, v246, s[100:101]
	v_cndmask_b32_e64 v244, v236, v246, vcc
	s_nop 0
	v_cndmask_b32_e64 v245, v237, v246, s[98:99]
	s_add_i32 s33, s33, 1
	s_cmp_lt_i32 s33, s3
	s_waitcnt lgkmcnt(0)
	v_mfma_f32_16x16x32_bf16 v[80:83], v[214:217], v[84:87], v[80:83]
	v_mfma_f32_16x16x32_bf16 v[76:79], v[218:221], v[84:87], v[76:79]
	v_mfma_f32_16x16x32_bf16 v[72:75], v[222:225], v[84:87], v[72:75]
	v_mfma_f32_16x16x32_bf16 v[68:71], v[226:229], v[84:87], v[68:71]
	s_cbranch_scc1 .LBB0_579
	s_branch .LBB0_585

.LBB0_585:
	v_cndmask_b32_e64 v0, 0, 1, s[42:43]
	v_cmp_ne_u32_e64 s[40:41], 1, v0
	s_andn2_b64 vcc, exec, s[42:43]
	s_barrier
	s_waitcnt vmcnt(3)
	ds_write_b128 v96, v[40:43] offset:36864
	s_waitcnt vmcnt(2)
	ds_write_b128 v96, v[48:51] offset:41088
	s_waitcnt vmcnt(1)
	ds_write_b128 v96, v[60:63] offset:45312
	s_waitcnt vmcnt(0)
	ds_write_b128 v96, v[64:67] offset:49536
	s_waitcnt lgkmcnt(0)
	s_barrier
	s_cbranch_vccnz .LBB0_589
	s_ashr_i32 s0, s2, 1
	s_max_i32 s3, s0, 16
	s_and_b64 s[0:1], s[38:39], exec
	s_cselect_b32 s0, 16, s3
	s_add_i32 s1, s2, 12
	s_ashr_i32 s1, s1, 1
	s_min_i32 s1, s1, 31
	s_and_b64 s[26:27], s[38:39], exec
	s_cselect_b32 s3, s1, 31
	s_cmp_gt_i32 s0, s3
	s_cbranch_scc1 .LBB0_589
	v_lshrrev_b32_e32 v2, 1, v95
	s_lshl_b32 s1, s0, 1
	s_add_i32 s33, s0, -1
	v_or_b32_e32 v0, s1, v2
	s_lshl_b32 s0, s0, 6
	v_sub_u32_e32 v0, v0, v88
	v_sub_u32_e32 v2, v88, v2
	v_add3_u32 v3, v92, s0, v94
	v_readlane_b32 s0, v253, 42
	v_add_u32_e32 v0, -12, v0
	v_subrev_u32_e32 v2, s1, v2
	v_add3_u32 v3, v3, v93, s0
	v_add_u32_e32 v234, 12, v0
	v_cndmask_b32_e64 v230, v234, v2, s[38:39]
	v_max_i32_e32 v242, 0, v230
	v_lshl_add_u32 v242, v242, 9, v91
	v_add_u32_e32 v235, 8, v0
	v_add_u32_e32 v239, 4, v2
	v_cndmask_b32_e64 v231, v235, v239, s[38:39]
	v_max_i32_e32 v243, 0, v231
	v_lshl_add_u32 v243, v243, 9, v91
	v_add_u32_e32 v236, 4, v0
	v_add_u32_e32 v240, 8, v2
	v_cndmask_b32_e64 v232, v236, v240, s[38:39]
	v_max_i32_e32 v244, 0, v232
	v_lshl_add_u32 v244, v244, 9, v91
	v_add_u32_e32 v241, 12, v2
	v_cndmask_b32_e64 v233, v0, v241, s[38:39]
	v_max_i32_e32 v245, 0, v233
	v_lshl_add_u32 v245, v245, 9, v91
	v_cmp_lt_i32_e64 s[98:99], -1, v230
	v_cmp_lt_i32_e64 s[100:101], -1, v231
	v_cmp_lt_i32_e64 vcc, -1, v232
	v_cndmask_b32_e64 v242, v246, v242, s[98:99]
	v_cmp_lt_i32_e64 s[98:99], -1, v233
	v_cndmask_b32_e64 v243, v246, v243, s[100:101]
	v_cndmask_b32_e64 v244, v246, v244, vcc
	s_nop 0
	v_cndmask_b32_e64 v245, v246, v245, s[98:99]
	v_lshl_add_u32 v234, v230, 9, v91
	v_lshl_add_u32 v235, v231, 9, v91
	v_lshl_add_u32 v236, v232, 9, v91
	v_lshl_add_u32 v237, v233, 9, v91
	v_mov_b32_e32 v238, 0x400
	v_mov_b32_e32 v239, 0xfffffc00
	v_cndmask_b32_e64 v238, v238, v239, s[38:39]
.LBB0_588:
	ds_read_b128 v[214:217], v242 offset:4096
	ds_read_b128 v[218:221], v243 offset:4096
	ds_read_b128 v[222:225], v244 offset:4096
	ds_read_b128 v[226:229], v245 offset:4096
	ds_read_b128 v[40:43], v3
	v_add_u32_e32 v0, 2, v0
	v_add_u32_e32 v2, -2, v2
	v_add_u32_e32 v3, 64, v3
	v_add_u32_e32 v234, v238, v234
	v_add_u32_e32 v235, v238, v235
	v_add_u32_e32 v236, v238, v236
	v_add_u32_e32 v237, v238, v237
	v_cmp_lt_i32_e64 s[98:99], v234, v91
	v_cmp_lt_i32_e64 s[100:101], v235, v91
	v_cmp_lt_i32_e64 vcc, v236, v91
	v_cndmask_b32_e64 v242, v234, v246, s[98:99]
	v_cmp_lt_i32_e64 s[98:99], v237, v91
	v_cndmask_b32_e64 v243, v235, v246, s[100:101]
	v_cndmask_b32_e64 v244, v236, v246, vcc
	s_nop 0
	v_cndmask_b32_e64 v245, v237, v246, s[98:99]
	s_add_i32 s33, s33, 1
	s_cmp_lt_i32 s33, s3
	s_waitcnt lgkmcnt(0)
	v_mfma_f32_16x16x32_bf16 v[16:19], v[214:217], v[40:43], v[16:19]
	v_mfma_f32_16x16x32_bf16 v[12:15], v[218:221], v[40:43], v[12:15]
	v_mfma_f32_16x16x32_bf16 v[8:11], v[222:225], v[40:43], v[8:11]
	v_mfma_f32_16x16x32_bf16 v[4:7], v[226:229], v[40:43], v[4:7]
	s_cbranch_scc1 .LBB0_588
.LBB0_589:
	v_cndmask_b32_e64 v0, 0, 1, s[44:45]
	v_cmp_ne_u32_e64 s[42:43], 1, v0
	s_andn2_b64 vcc, exec, s[44:45]
	s_cbranch_vccnz .LBB0_593
	s_add_i32 s0, s2, 16
	s_ashr_i32 s0, s0, 1
	s_max_i32 s3, s0, 16
	s_and_b64 s[0:1], s[38:39], exec
	s_cselect_b32 s0, 16, s3
	s_add_i32 s1, s2, 28
	s_ashr_i32 s1, s1, 1
	s_min_i32 s1, s1, 31
	s_and_b64 s[26:27], s[38:39], exec
	s_cselect_b32 s3, s1, 31
	s_cmp_gt_i32 s0, s3
	s_cbranch_scc1 .LBB0_593
	v_lshrrev_b32_e32 v2, 1, v95
	s_lshl_b32 s1, s0, 1
	s_add_i32 s33, s0, -1
	v_or_b32_e32 v0, s1, v2
	v_sub_u32_e32 v2, v88, v2
	s_lshl_b32 s0, s0, 6
	v_sub_u32_e32 v0, v0, v88
	v_subrev_u32_e32 v2, s1, v2
	v_add3_u32 v3, v92, s0, v94
	v_readlane_b32 s0, v253, 42
	v_subrev_u32_e32 v0, 28, v0
	v_add_u32_e32 v2, 28, v2
	v_add3_u32 v3, v3, v93, s0
	v_add_u32_e32 v234, 12, v0
	v_add_u32_e32 v238, -12, v2
	v_cndmask_b32_e64 v230, v234, v238, s[38:39]
	v_max_i32_e32 v242, 0, v230
	v_lshl_add_u32 v242, v242, 9, v91
	v_add_u32_e32 v235, 8, v0
	v_add_u32_e32 v239, -8, v2
	v_cndmask_b32_e64 v231, v235, v239, s[38:39]
	v_max_i32_e32 v243, 0, v231
	v_lshl_add_u32 v243, v243, 9, v91
	v_add_u32_e32 v236, 4, v0
	v_add_u32_e32 v240, -4, v2
	v_cndmask_b32_e64 v232, v236, v240, s[38:39]
	v_max_i32_e32 v244, 0, v232
	v_lshl_add_u32 v244, v244, 9, v91
	v_cndmask_b32_e64 v233, v0, v2, s[38:39]
	v_max_i32_e32 v245, 0, v233
	v_lshl_add_u32 v245, v245, 9, v91
	v_cmp_lt_i32_e64 s[98:99], -1, v230
	v_cmp_lt_i32_e64 s[100:101], -1, v231
	v_cmp_lt_i32_e64 vcc, -1, v232
	v_cndmask_b32_e64 v242, v246, v242, s[98:99]
	v_cmp_lt_i32_e64 s[98:99], -1, v233
	v_cndmask_b32_e64 v243, v246, v243, s[100:101]
	v_cndmask_b32_e64 v244, v246, v244, vcc
	s_nop 0
	v_cndmask_b32_e64 v245, v246, v245, s[98:99]
	v_lshl_add_u32 v234, v230, 9, v91
	v_lshl_add_u32 v235, v231, 9, v91
	v_lshl_add_u32 v236, v232, 9, v91
	v_lshl_add_u32 v237, v233, 9, v91
	v_mov_b32_e32 v238, 0x400
	v_mov_b32_e32 v239, 0xfffffc00
	v_cndmask_b32_e64 v238, v238, v239, s[38:39]
.LBB0_592:
	ds_read_b128 v[214:217], v242 offset:4096
	ds_read_b128 v[218:221], v243 offset:4096
	ds_read_b128 v[222:225], v244 offset:4096
	ds_read_b128 v[226:229], v245 offset:4096
	ds_read_b128 v[40:43], v3
	v_add_u32_e32 v0, 2, v0
	v_add_u32_e32 v2, -2, v2
	v_add_u32_e32 v3, 64, v3
	v_add_u32_e32 v234, v238, v234
	v_add_u32_e32 v235, v238, v235
	v_add_u32_e32 v236, v238, v236
	v_add_u32_e32 v237, v238, v237
	v_cmp_lt_i32_e64 s[98:99], v234, v91
	v_cmp_lt_i32_e64 s[100:101], v235, v91
	v_cmp_lt_i32_e64 vcc, v236, v91
	v_cndmask_b32_e64 v242, v234, v246, s[98:99]
	v_cmp_lt_i32_e64 s[98:99], v237, v91
	v_cndmask_b32_e64 v243, v235, v246, s[100:101]
	v_cndmask_b32_e64 v244, v236, v246, vcc
	s_nop 0
	v_cndmask_b32_e64 v245, v237, v246, s[98:99]
	s_add_i32 s33, s33, 1
	s_cmp_lt_i32 s33, s3
	s_waitcnt lgkmcnt(0)
	v_mfma_f32_16x16x32_bf16 v[32:35], v[214:217], v[40:43], v[32:35]
	v_mfma_f32_16x16x32_bf16 v[28:31], v[218:221], v[40:43], v[28:31]
	v_mfma_f32_16x16x32_bf16 v[24:27], v[222:225], v[40:43], v[24:27]
	v_mfma_f32_16x16x32_bf16 v[20:23], v[226:229], v[40:43], v[20:23]
	s_cbranch_scc1 .LBB0_592
.LBB0_593:
	v_cndmask_b32_e64 v0, 0, 1, s[46:47]
	v_cmp_ne_u32_e64 s[44:45], 1, v0
	s_andn2_b64 vcc, exec, s[46:47]
	s_cbranch_vccnz .LBB0_597
	s_add_i32 s0, s2, 32
	s_ashr_i32 s0, s0, 1
	s_max_i32 s3, s0, 16
	s_and_b64 s[0:1], s[38:39], exec
	s_cselect_b32 s0, 16, s3
	s_add_i32 s1, s2, 44
	s_ashr_i32 s1, s1, 1
	s_min_i32 s1, s1, 31
	s_and_b64 s[26:27], s[38:39], exec
	s_cselect_b32 s3, s1, 31
	s_cmp_gt_i32 s0, s3
	s_cbranch_scc1 .LBB0_597
	v_lshrrev_b32_e32 v2, 1, v95
	s_lshl_b32 s1, s0, 1
	s_add_i32 s33, s0, -1
	v_or_b32_e32 v0, s1, v2
	v_sub_u32_e32 v2, v88, v2
	s_lshl_b32 s0, s0, 6
	v_sub_u32_e32 v0, v0, v88
	v_subrev_u32_e32 v2, s1, v2
	v_add3_u32 v3, v92, s0, v94
	v_readlane_b32 s0, v253, 42
	v_subrev_u32_e32 v0, 44, v0
	v_add_u32_e32 v2, 44, v2
	v_add3_u32 v3, v3, v93, s0
	v_add_u32_e32 v234, 12, v0
	v_add_u32_e32 v238, -12, v2
	v_cndmask_b32_e64 v230, v234, v238, s[38:39]
	v_max_i32_e32 v242, 0, v230
	v_lshl_add_u32 v242, v242, 9, v91
	v_add_u32_e32 v235, 8, v0
	v_add_u32_e32 v239, -8, v2
	v_cndmask_b32_e64 v231, v235, v239, s[38:39]
	v_max_i32_e32 v243, 0, v231
	v_lshl_add_u32 v243, v243, 9, v91
	v_add_u32_e32 v236, 4, v0
	v_add_u32_e32 v240, -4, v2
	v_cndmask_b32_e64 v232, v236, v240, s[38:39]
	v_max_i32_e32 v244, 0, v232
	v_lshl_add_u32 v244, v244, 9, v91
	v_cndmask_b32_e64 v233, v0, v2, s[38:39]
	v_max_i32_e32 v245, 0, v233
	v_lshl_add_u32 v245, v245, 9, v91
	v_cmp_lt_i32_e64 s[98:99], -1, v230
	v_cmp_lt_i32_e64 s[100:101], -1, v231
	v_cmp_lt_i32_e64 vcc, -1, v232
	v_cndmask_b32_e64 v242, v246, v242, s[98:99]
	v_cmp_lt_i32_e64 s[98:99], -1, v233
	v_cndmask_b32_e64 v243, v246, v243, s[100:101]
	v_cndmask_b32_e64 v244, v246, v244, vcc
	s_nop 0
	v_cndmask_b32_e64 v245, v246, v245, s[98:99]
	v_lshl_add_u32 v234, v230, 9, v91
	v_lshl_add_u32 v235, v231, 9, v91
	v_lshl_add_u32 v236, v232, 9, v91
	v_lshl_add_u32 v237, v233, 9, v91
	v_mov_b32_e32 v238, 0x400
	v_mov_b32_e32 v239, 0xfffffc00
	v_cndmask_b32_e64 v238, v238, v239, s[38:39]
.LBB0_596:
	ds_read_b128 v[214:217], v242 offset:4096
	ds_read_b128 v[218:221], v243 offset:4096
	ds_read_b128 v[222:225], v244 offset:4096
	ds_read_b128 v[226:229], v245 offset:4096
	ds_read_b128 v[40:43], v3
	v_add_u32_e32 v0, 2, v0
	v_add_u32_e32 v2, -2, v2
	v_add_u32_e32 v3, 64, v3
	v_add_u32_e32 v234, v238, v234
	v_add_u32_e32 v235, v238, v235
	v_add_u32_e32 v236, v238, v236
	v_add_u32_e32 v237, v238, v237
	v_cmp_lt_i32_e64 s[98:99], v234, v91
	v_cmp_lt_i32_e64 s[100:101], v235, v91
	v_cmp_lt_i32_e64 vcc, v236, v91
	v_cndmask_b32_e64 v242, v234, v246, s[98:99]
	v_cmp_lt_i32_e64 s[98:99], v237, v91
	v_cndmask_b32_e64 v243, v235, v246, s[100:101]
	v_cndmask_b32_e64 v244, v236, v246, vcc
	s_nop 0
	v_cndmask_b32_e64 v245, v237, v246, s[98:99]
	s_add_i32 s33, s33, 1
	s_cmp_lt_i32 s33, s3
	s_waitcnt lgkmcnt(0)
	v_mfma_f32_16x16x32_bf16 v[56:59], v[214:217], v[40:43], v[56:59]
	v_mfma_f32_16x16x32_bf16 v[52:55], v[218:221], v[40:43], v[52:55]
	v_mfma_f32_16x16x32_bf16 v[44:47], v[222:225], v[40:43], v[44:47]
	v_mfma_f32_16x16x32_bf16 v[36:39], v[226:229], v[40:43], v[36:39]
	s_cbranch_scc1 .LBB0_596
.LBB0_597:
	v_cndmask_b32_e64 v0, 0, 1, s[52:53]
	v_cmp_ne_u32_e64 s[46:47], 1, v0
	s_andn2_b64 vcc, exec, s[52:53]
	s_cbranch_vccnz .LBB0_601
	s_add_i32 s0, s2, 48
	s_ashr_i32 s0, s0, 1
	s_max_i32 s3, s0, 16
	s_and_b64 s[0:1], s[38:39], exec
	s_cselect_b32 s0, 16, s3
	s_add_i32 s2, s2, 60
	s_ashr_i32 s1, s2, 1
	s_min_i32 s1, s1, 31
	s_and_b64 s[2:3], s[38:39], exec
	s_cselect_b32 s2, s1, 31
	s_cmp_gt_i32 s0, s2
	s_cbranch_scc1 .LBB0_601
	v_lshrrev_b32_e32 v2, 1, v95
	s_lshl_b32 s1, s0, 1
	s_add_i32 s3, s0, -1
	v_or_b32_e32 v0, s1, v2
	v_sub_u32_e32 v2, v88, v2
	s_lshl_b32 s0, s0, 6
	v_sub_u32_e32 v0, v0, v88
	v_subrev_u32_e32 v2, s1, v2
	v_add3_u32 v3, v92, s0, v94
	v_readlane_b32 s0, v253, 42
	v_subrev_u32_e32 v0, 60, v0
	v_add_u32_e32 v2, 60, v2
	v_add3_u32 v3, v3, v93, s0
	v_add_u32_e32 v234, 12, v0
	v_add_u32_e32 v238, -12, v2
	v_cndmask_b32_e64 v230, v234, v238, s[38:39]
	v_max_i32_e32 v242, 0, v230
	v_lshl_add_u32 v242, v242, 9, v91
	v_add_u32_e32 v235, 8, v0
	v_add_u32_e32 v239, -8, v2
	v_cndmask_b32_e64 v231, v235, v239, s[38:39]
	v_max_i32_e32 v243, 0, v231
	v_lshl_add_u32 v243, v243, 9, v91
	v_add_u32_e32 v236, 4, v0
	v_add_u32_e32 v240, -4, v2
	v_cndmask_b32_e64 v232, v236, v240, s[38:39]
	v_max_i32_e32 v244, 0, v232
	v_lshl_add_u32 v244, v244, 9, v91
	v_cndmask_b32_e64 v233, v0, v2, s[38:39]
	v_max_i32_e32 v245, 0, v233
	v_lshl_add_u32 v245, v245, 9, v91
	v_cmp_lt_i32_e64 s[98:99], -1, v230
	v_cmp_lt_i32_e64 s[100:101], -1, v231
	v_cmp_lt_i32_e64 vcc, -1, v232
	v_cndmask_b32_e64 v242, v246, v242, s[98:99]
	v_cmp_lt_i32_e64 s[98:99], -1, v233
	v_cndmask_b32_e64 v243, v246, v243, s[100:101]
	v_cndmask_b32_e64 v244, v246, v244, vcc
	s_nop 0
	v_cndmask_b32_e64 v245, v246, v245, s[98:99]
	v_lshl_add_u32 v234, v230, 9, v91
	v_lshl_add_u32 v235, v231, 9, v91
	v_lshl_add_u32 v236, v232, 9, v91
	v_lshl_add_u32 v237, v233, 9, v91
	v_mov_b32_e32 v238, 0x400
	v_mov_b32_e32 v239, 0xfffffc00
	v_cndmask_b32_e64 v238, v238, v239, s[38:39]
.LBB0_600:
	ds_read_b128 v[214:217], v242 offset:4096
	ds_read_b128 v[218:221], v243 offset:4096
	ds_read_b128 v[222:225], v244 offset:4096
	ds_read_b128 v[226:229], v245 offset:4096
	ds_read_b128 v[40:43], v3
	v_add_u32_e32 v0, 2, v0
	v_add_u32_e32 v2, -2, v2
	v_add_u32_e32 v3, 64, v3
	v_add_u32_e32 v234, v238, v234
	v_add_u32_e32 v235, v238, v235
	v_add_u32_e32 v236, v238, v236
	v_add_u32_e32 v237, v238, v237
	v_cmp_lt_i32_e64 s[98:99], v234, v91
	v_cmp_lt_i32_e64 s[100:101], v235, v91
	v_cmp_lt_i32_e64 vcc, v236, v91
	v_cndmask_b32_e64 v242, v234, v246, s[98:99]
	v_cmp_lt_i32_e64 s[98:99], v237, v91
	v_cndmask_b32_e64 v243, v235, v246, s[100:101]
	v_cndmask_b32_e64 v244, v236, v246, vcc
	s_nop 0
	v_cndmask_b32_e64 v245, v237, v246, s[98:99]
	s_add_i32 s3, s3, 1
	s_cmp_lt_i32 s3, s2
	s_waitcnt lgkmcnt(0)
	v_mfma_f32_16x16x32_bf16 v[80:83], v[214:217], v[40:43], v[80:83]
	v_mfma_f32_16x16x32_bf16 v[76:79], v[218:221], v[40:43], v[76:79]
	v_mfma_f32_16x16x32_bf16 v[72:75], v[222:225], v[40:43], v[72:75]
	v_mfma_f32_16x16x32_bf16 v[68:71], v[226:229], v[40:43], v[68:71]
	s_cbranch_scc1 .LBB0_600

.LBB0_715:
	s_or_b64 exec, exec, s[40:41]
	s_waitcnt vmcnt(31)
	v_and_b32_e32 v93, 15, v50
	v_or_b32_e32 v18, s2, v93
	v_mul_lo_u16_sdwa v0, v18, v204 dst_sel:DWORD dst_unused:UNUSED_PAD src0_sel:BYTE_0 src1_sel:DWORD
	v_lshrrev_b16_e32 v0, 11, v0
	v_mul_lo_u16_e32 v19, 36, v0
	v_sub_u16_e32 v18, v18, v19
	v_cmp_gt_u16_sdwa s[0:1], v18, v205 src0_sel:BYTE_0 src1_sel:DWORD
	v_lshlrev_b32_sdwa v18, v206, v18 dst_sel:DWORD dst_unused:UNUSED_PAD src0_sel:DWORD src1_sel:BYTE_0
	s_and_saveexec_b64 s[2:3], s[0:1]
	s_xor_b64 s[38:39], exec, s[2:3]
	v_lshlrev_b32_e32 v0, 11, v0
	s_movk_i32 s0, 0xff00
	v_add3_u32 v100, v0, v18, s0
	s_andn2_saveexec_b64 s[38:39], s[38:39]
	v_lshlrev_b32_e32 v0, 8, v0
	v_or3_b32 v100, v0, v18, s74
	s_or_b64 exec, exec, s[38:39]
	v_readfirstlane_b32 s41, v88
	s_movk_i32 s0, 0x420
	s_ashr_i32 s2, s41, 1
	v_mad_u32_u24 v18, v93, s0, 0
	v_lshlrev_b32_e32 v19, 10, v93
	s_max_i32 s3, s2, 0
	v_sub_u32_e32 v95, v18, v19
	v_mul_lo_u32 v18, v88, s0
	s_and_b64 s[0:1], vcc, exec
	s_cselect_b32 s0, 0, s3
	s_add_i32 s1, s41, 12
	s_ashr_i32 s3, s1, 1
	v_bfe_u32 v0, v50, 4, 2
	v_lshlrev_b32_e32 v19, 4, v50
	s_min_i32 s1, s3, 15
	v_lshlrev_b32_e32 v90, 4, v0
	v_and_b32_e32 v20, 0x3e0, v19
	s_and_b64 s[26:27], vcc, exec
	v_and_b32_e32 v97, 16, v90
	v_add3_u32 v18, 0, v18, v20
	v_and_b32_e32 v19, 16, v19
	s_cselect_b32 s19, s1, 15
	v_lshrrev_b32_e32 v101, 1, v0
	v_mul_u32_u24_e32 v91, 0x420, v93
	v_and_b32_e32 v99, 32, v90
	s_waitcnt vmcnt(29)
	v_add_u32_e32 v89, v95, v97
	v_add_u32_e32 v94, v18, v19
	s_cmp_gt_i32 s0, s19
	v_sub_u32_e32 v92, v88, v101
	s_waitcnt lgkmcnt(0)
	s_barrier
	s_waitcnt vmcnt(7)
	ds_write_b128 v94, v[2:5] offset:36864
	s_waitcnt vmcnt(6)
	ds_write_b128 v94, v[6:9] offset:41088
	s_waitcnt vmcnt(5)
	ds_write_b128 v94, v[10:13] offset:45312
	s_waitcnt vmcnt(4)
	ds_write_b128 v94, v[14:17] offset:49536
	s_waitcnt lgkmcnt(0)
	s_barrier
	s_cbranch_scc1 .LBB0_722
	s_lshl_b32 s1, s0, 1
	s_add_i32 s33, s0, -1
	v_or_b32_e32 v0, s1, v101
	s_lshl_b32 s0, s0, 6
	v_sub_u32_e32 v0, v0, v88
	v_add3_u32 v3, v91, s0, v99
	s_add_i32 s0, 0, 0x9000
	v_mov_b32_e32 v4, 0
	v_add_u32_e32 v0, -12, v0
	v_subrev_u32_e32 v2, s1, v92
	v_add3_u32 v3, v3, v97, s0
	v_mov_b32_e32 v5, v4
	v_mov_b32_e32 v6, v4
	v_mov_b32_e32 v7, v4
	v_mov_b32_e32 v8, v4
	v_mov_b32_e32 v9, v4
	v_mov_b32_e32 v10, v4
	v_mov_b32_e32 v11, v4
	v_mov_b32_e32 v12, v4
	v_mov_b32_e32 v13, v4
	v_mov_b32_e32 v14, v4
	v_mov_b32_e32 v15, v4
	v_mov_b32_e32 v16, v4
	v_mov_b32_e32 v17, v4
	v_mov_b32_e32 v18, v4
	v_mov_b32_e32 v19, v4
	v_add_u32_e32 v234, 12, v0
	v_cndmask_b32_e64 v230, v234, v2, vcc
	v_max_i32_e32 v242, 0, v230
	v_lshl_add_u32 v242, v242, 9, v89
	v_add_u32_e32 v235, 8, v0
	v_add_u32_e32 v239, 4, v2
	v_cndmask_b32_e64 v231, v235, v239, vcc
	v_max_i32_e32 v243, 0, v231
	v_lshl_add_u32 v243, v243, 9, v89
	v_add_u32_e32 v236, 4, v0
	v_add_u32_e32 v240, 8, v2
	v_cndmask_b32_e64 v232, v236, v240, vcc
	v_max_i32_e32 v244, 0, v232
	v_lshl_add_u32 v244, v244, 9, v89
	v_add_u32_e32 v241, 12, v2
	v_cndmask_b32_e64 v233, v0, v241, vcc
	v_max_i32_e32 v245, 0, v233
	v_lshl_add_u32 v245, v245, 9, v89
	v_cmp_lt_i32_e64 s[98:99], -1, v230
	v_cmp_lt_i32_e64 s[100:101], -1, v231
	v_cmp_lt_i32_e64 s[38:39], -1, v232
	v_cndmask_b32_e64 v242, v246, v242, s[98:99]
	v_cmp_lt_i32_e64 s[98:99], -1, v233
	v_cndmask_b32_e64 v243, v246, v243, s[100:101]
	v_cndmask_b32_e64 v244, v246, v244, s[38:39]
	s_nop 0
	v_cndmask_b32_e64 v245, v246, v245, s[98:99]
	v_lshl_add_u32 v234, v230, 9, v89
	v_lshl_add_u32 v235, v231, 9, v89
	v_lshl_add_u32 v236, v232, 9, v89
	v_lshl_add_u32 v237, v233, 9, v89
	v_mov_b32_e32 v238, 0x400
	v_mov_b32_e32 v239, 0xfffffc00
	v_cndmask_b32_e64 v238, v238, v239, vcc
.LBB0_721:
	ds_read_b128 v[214:217], v242 offset:4096
	ds_read_b128 v[218:221], v243 offset:4096
	ds_read_b128 v[222:225], v244 offset:4096
	ds_read_b128 v[226:229], v245 offset:4096
	ds_read_b128 v[20:23], v3
	v_add_u32_e32 v0, 2, v0
	v_add_u32_e32 v2, -2, v2
	v_add_u32_e32 v3, 64, v3
	v_add_u32_e32 v234, v238, v234
	v_add_u32_e32 v235, v238, v235
	v_add_u32_e32 v236, v238, v236
	v_add_u32_e32 v237, v238, v237
	v_cmp_lt_i32_e64 s[98:99], v234, v89
	v_cmp_lt_i32_e64 s[100:101], v235, v89
	v_cmp_lt_i32_e64 s[38:39], v236, v89
	v_cndmask_b32_e64 v242, v234, v246, s[98:99]
	v_cmp_lt_i32_e64 s[98:99], v237, v89
	v_cndmask_b32_e64 v243, v235, v246, s[100:101]
	v_cndmask_b32_e64 v244, v236, v246, s[38:39]
	s_nop 0
	v_cndmask_b32_e64 v245, v237, v246, s[98:99]
	s_add_i32 s33, s33, 1
	s_cmp_lt_i32 s33, s19
	s_waitcnt lgkmcnt(0)
	v_mfma_f32_16x16x32_bf16 v[16:19], v[214:217], v[20:23], v[16:19]
	v_mfma_f32_16x16x32_bf16 v[12:15], v[218:221], v[20:23], v[12:15]
	v_mfma_f32_16x16x32_bf16 v[8:11], v[222:225], v[20:23], v[8:11]
	v_mfma_f32_16x16x32_bf16 v[4:7], v[226:229], v[20:23], v[4:7]
	s_cbranch_scc1 .LBB0_721
	s_branch .LBB0_723

.LBB0_723:
	s_add_i32 s0, s41, 16
	s_ashr_i32 s19, s0, 1
	s_max_i32 s26, s19, 0
	s_and_b64 s[0:1], vcc, exec
	s_cselect_b32 s0, 0, s26
	s_add_i32 s1, s41, 28
	s_ashr_i32 s33, s1, 1
	s_min_i32 s1, s33, 15
	s_and_b64 s[26:27], vcc, exec
	s_cselect_b32 s36, s1, 15
	s_cmp_gt_i32 s0, s36
	s_cbranch_scc1 .LBB0_726
	s_lshl_b32 s1, s0, 1
	s_add_i32 s37, s0, -1
	v_or_b32_e32 v0, s1, v101
	s_lshl_b32 s0, s0, 6
	v_sub_u32_e32 v0, v0, v88
	v_subrev_u32_e32 v2, s1, v92
	v_add3_u32 v3, v91, s0, v99
	s_add_i32 s0, 0, 0x9000
	v_mov_b32_e32 v20, 0
	v_subrev_u32_e32 v0, 28, v0
	v_add_u32_e32 v2, 28, v2
	v_add3_u32 v3, v3, v97, s0
	v_mov_b32_e32 v21, v20
	v_mov_b32_e32 v22, v20
	v_mov_b32_e32 v23, v20
	v_mov_b32_e32 v24, v20
	v_mov_b32_e32 v25, v20
	v_mov_b32_e32 v26, v20
	v_mov_b32_e32 v27, v20
	v_mov_b32_e32 v28, v20
	v_mov_b32_e32 v29, v20
	v_mov_b32_e32 v30, v20
	v_mov_b32_e32 v31, v20
	v_mov_b32_e32 v32, v20
	v_mov_b32_e32 v33, v20
	v_mov_b32_e32 v34, v20
	v_mov_b32_e32 v35, v20
	v_add_u32_e32 v234, 12, v0
	v_add_u32_e32 v238, -12, v2
	v_cndmask_b32_e64 v230, v234, v238, vcc
	v_max_i32_e32 v242, 0, v230
	v_lshl_add_u32 v242, v242, 9, v89
	v_add_u32_e32 v235, 8, v0
	v_add_u32_e32 v239, -8, v2
	v_cndmask_b32_e64 v231, v235, v239, vcc
	v_max_i32_e32 v243, 0, v231
	v_lshl_add_u32 v243, v243, 9, v89
	v_add_u32_e32 v236, 4, v0
	v_add_u32_e32 v240, -4, v2
	v_cndmask_b32_e64 v232, v236, v240, vcc
	v_max_i32_e32 v244, 0, v232
	v_lshl_add_u32 v244, v244, 9, v89
	v_cndmask_b32_e64 v233, v0, v2, vcc
	v_max_i32_e32 v245, 0, v233
	v_lshl_add_u32 v245, v245, 9, v89
	v_cmp_lt_i32_e64 s[98:99], -1, v230
	v_cmp_lt_i32_e64 s[100:101], -1, v231
	v_cmp_lt_i32_e64 s[38:39], -1, v232
	v_cndmask_b32_e64 v242, v246, v242, s[98:99]
	v_cmp_lt_i32_e64 s[98:99], -1, v233
	v_cndmask_b32_e64 v243, v246, v243, s[100:101]
	v_cndmask_b32_e64 v244, v246, v244, s[38:39]
	s_nop 0
	v_cndmask_b32_e64 v245, v246, v245, s[98:99]
	v_lshl_add_u32 v234, v230, 9, v89
	v_lshl_add_u32 v235, v231, 9, v89
	v_lshl_add_u32 v236, v232, 9, v89
	v_lshl_add_u32 v237, v233, 9, v89
	v_mov_b32_e32 v238, 0x400
	v_mov_b32_e32 v239, 0xfffffc00
	v_cndmask_b32_e64 v238, v238, v239, vcc
.LBB0_725:
	ds_read_b128 v[214:217], v242 offset:4096
	ds_read_b128 v[218:221], v243 offset:4096
	ds_read_b128 v[222:225], v244 offset:4096
	ds_read_b128 v[226:229], v245 offset:4096
	ds_read_b128 v[36:39], v3
	v_add_u32_e32 v0, 2, v0
	v_add_u32_e32 v2, -2, v2
	v_add_u32_e32 v3, 64, v3
	v_add_u32_e32 v234, v238, v234
	v_add_u32_e32 v235, v238, v235
	v_add_u32_e32 v236, v238, v236
	v_add_u32_e32 v237, v238, v237
	v_cmp_lt_i32_e64 s[98:99], v234, v89
	v_cmp_lt_i32_e64 s[100:101], v235, v89
	v_cmp_lt_i32_e64 s[38:39], v236, v89
	v_cndmask_b32_e64 v242, v234, v246, s[98:99]
	v_cmp_lt_i32_e64 s[98:99], v237, v89
	v_cndmask_b32_e64 v243, v235, v246, s[100:101]
	v_cndmask_b32_e64 v244, v236, v246, s[38:39]
	s_nop 0
	v_cndmask_b32_e64 v245, v237, v246, s[98:99]
	s_add_i32 s37, s37, 1
	s_cmp_lt_i32 s37, s36
	s_waitcnt lgkmcnt(0)
	v_mfma_f32_16x16x32_bf16 v[32:35], v[214:217], v[36:39], v[32:35]
	v_mfma_f32_16x16x32_bf16 v[28:31], v[218:221], v[36:39], v[28:31]
	v_mfma_f32_16x16x32_bf16 v[24:27], v[222:225], v[36:39], v[24:27]
	v_mfma_f32_16x16x32_bf16 v[20:23], v[226:229], v[36:39], v[20:23]
	s_cbranch_scc1 .LBB0_725
	s_branch .LBB0_727

.LBB0_727:
	s_add_i32 s0, s41, 32
	s_ashr_i32 s36, s0, 1
	s_max_i32 s26, s36, 0
	s_and_b64 s[0:1], vcc, exec
	s_cselect_b32 s0, 0, s26
	s_add_i32 s1, s41, 44
	s_ashr_i32 s37, s1, 1
	s_min_i32 s1, s37, 15
	s_and_b64 s[26:27], vcc, exec
	s_cselect_b32 s40, s1, 15
	s_cmp_gt_i32 s0, s40
	s_cbranch_scc1 .LBB0_730
	s_lshl_b32 s1, s0, 1
	s_add_i32 s42, s0, -1
	v_or_b32_e32 v0, s1, v101
	s_lshl_b32 s0, s0, 6
	v_sub_u32_e32 v0, v0, v88
	v_subrev_u32_e32 v2, s1, v92
	v_add3_u32 v3, v91, s0, v99
	s_add_i32 s0, 0, 0x9000
	v_mov_b32_e32 v36, 0
	v_subrev_u32_e32 v0, 44, v0
	v_add_u32_e32 v2, 44, v2
	v_add3_u32 v3, v3, v97, s0
	v_mov_b32_e32 v37, v36
	v_mov_b32_e32 v38, v36
	v_mov_b32_e32 v39, v36
	v_mov_b32_e32 v40, v36
	v_mov_b32_e32 v41, v36
	v_mov_b32_e32 v42, v36
	v_mov_b32_e32 v43, v36
	v_mov_b32_e32 v44, v36
	v_mov_b32_e32 v45, v36
	v_mov_b32_e32 v46, v36
	v_mov_b32_e32 v47, v36
	v_mov_b32_e32 v48, v36
	v_mov_b32_e32 v49, v36
	v_mov_b32_e32 v50, v36
	v_mov_b32_e32 v51, v36
	v_add_u32_e32 v234, 12, v0
	v_add_u32_e32 v238, -12, v2
	v_cndmask_b32_e64 v230, v234, v238, vcc
	v_max_i32_e32 v242, 0, v230
	v_lshl_add_u32 v242, v242, 9, v89
	v_add_u32_e32 v235, 8, v0
	v_add_u32_e32 v239, -8, v2
	v_cndmask_b32_e64 v231, v235, v239, vcc
	v_max_i32_e32 v243, 0, v231
	v_lshl_add_u32 v243, v243, 9, v89
	v_add_u32_e32 v236, 4, v0
	v_add_u32_e32 v240, -4, v2
	v_cndmask_b32_e64 v232, v236, v240, vcc
	v_max_i32_e32 v244, 0, v232
	v_lshl_add_u32 v244, v244, 9, v89
	v_cndmask_b32_e64 v233, v0, v2, vcc
	v_max_i32_e32 v245, 0, v233
	v_lshl_add_u32 v245, v245, 9, v89
	v_cmp_lt_i32_e64 s[98:99], -1, v230
	v_cmp_lt_i32_e64 s[100:101], -1, v231
	v_cmp_lt_i32_e64 s[38:39], -1, v232
	v_cndmask_b32_e64 v242, v246, v242, s[98:99]
	v_cmp_lt_i32_e64 s[98:99], -1, v233
	v_cndmask_b32_e64 v243, v246, v243, s[100:101]
	v_cndmask_b32_e64 v244, v246, v244, s[38:39]
	s_nop 0
	v_cndmask_b32_e64 v245, v246, v245, s[98:99]
	v_lshl_add_u32 v234, v230, 9, v89
	v_lshl_add_u32 v235, v231, 9, v89
	v_lshl_add_u32 v236, v232, 9, v89
	v_lshl_add_u32 v237, v233, 9, v89
	v_mov_b32_e32 v238, 0x400
	v_mov_b32_e32 v239, 0xfffffc00
	v_cndmask_b32_e64 v238, v238, v239, vcc
.LBB0_729:
	ds_read_b128 v[214:217], v242 offset:4096
	ds_read_b128 v[218:221], v243 offset:4096
	ds_read_b128 v[222:225], v244 offset:4096
	ds_read_b128 v[226:229], v245 offset:4096
	ds_read_b128 v[68:71], v3
	v_add_u32_e32 v0, 2, v0
	v_add_u32_e32 v2, -2, v2
	v_add_u32_e32 v3, 64, v3
	v_add_u32_e32 v234, v238, v234
	v_add_u32_e32 v235, v238, v235
	v_add_u32_e32 v236, v238, v236
	v_add_u32_e32 v237, v238, v237
	v_cmp_lt_i32_e64 s[98:99], v234, v89
	v_cmp_lt_i32_e64 s[100:101], v235, v89
	v_cmp_lt_i32_e64 s[38:39], v236, v89
	v_cndmask_b32_e64 v242, v234, v246, s[98:99]
	v_cmp_lt_i32_e64 s[98:99], v237, v89
	v_cndmask_b32_e64 v243, v235, v246, s[100:101]
	v_cndmask_b32_e64 v244, v236, v246, s[38:39]
	s_nop 0
	v_cndmask_b32_e64 v245, v237, v246, s[98:99]
	s_add_i32 s42, s42, 1
	s_cmp_lt_i32 s42, s40
	s_waitcnt lgkmcnt(0)
	v_mfma_f32_16x16x32_bf16 v[48:51], v[214:217], v[68:71], v[48:51]
	v_mfma_f32_16x16x32_bf16 v[44:47], v[218:221], v[68:71], v[44:47]
	v_mfma_f32_16x16x32_bf16 v[40:43], v[222:225], v[68:71], v[40:43]
	v_mfma_f32_16x16x32_bf16 v[36:39], v[226:229], v[68:71], v[36:39]
	s_cbranch_scc1 .LBB0_729
	s_branch .LBB0_731

.LBB0_731:
	s_add_i32 s0, s41, 48
	s_ashr_i32 s40, s0, 1
	s_max_i32 s26, s40, 0
	s_and_b64 s[0:1], vcc, exec
	s_cselect_b32 s0, 0, s26
	s_add_i32 s41, s41, 60
	s_ashr_i32 s41, s41, 1
	s_min_i32 s1, s41, 15
	s_and_b64 s[26:27], vcc, exec
	s_cselect_b32 s42, s1, 15
	s_cmp_gt_i32 s0, s42
	s_cbranch_scc1 .LBB0_734
	s_lshl_b32 s1, s0, 1
	s_add_i32 s43, s0, -1
	v_or_b32_e32 v0, s1, v101
	s_lshl_b32 s0, s0, 6
	v_sub_u32_e32 v0, v0, v88
	v_subrev_u32_e32 v2, s1, v92
	v_add3_u32 v3, v91, s0, v99
	s_add_i32 s0, 0, 0x9000
	v_mov_b32_e32 v68, 0
	v_subrev_u32_e32 v0, 60, v0
	v_add_u32_e32 v2, 60, v2
	v_add3_u32 v3, v3, v97, s0
	v_mov_b32_e32 v69, v68
	v_mov_b32_e32 v70, v68
	v_mov_b32_e32 v71, v68
	v_mov_b32_e32 v72, v68
	v_mov_b32_e32 v73, v68
	v_mov_b32_e32 v74, v68
	v_mov_b32_e32 v75, v68
	v_mov_b32_e32 v76, v68
	v_mov_b32_e32 v77, v68
	v_mov_b32_e32 v78, v68
	v_mov_b32_e32 v79, v68
	v_mov_b32_e32 v80, v68
	v_mov_b32_e32 v81, v68
	v_mov_b32_e32 v82, v68
	v_mov_b32_e32 v83, v68
	v_add_u32_e32 v234, 12, v0
	v_add_u32_e32 v238, -12, v2
	v_cndmask_b32_e64 v230, v234, v238, vcc
	v_max_i32_e32 v242, 0, v230
	v_lshl_add_u32 v242, v242, 9, v89
	v_add_u32_e32 v235, 8, v0
	v_add_u32_e32 v239, -8, v2
	v_cndmask_b32_e64 v231, v235, v239, vcc
	v_max_i32_e32 v243, 0, v231
	v_lshl_add_u32 v243, v243, 9, v89
	v_add_u32_e32 v236, 4, v0
	v_add_u32_e32 v240, -4, v2
	v_cndmask_b32_e64 v232, v236, v240, vcc
	v_max_i32_e32 v244, 0, v232
	v_lshl_add_u32 v244, v244, 9, v89
	v_cndmask_b32_e64 v233, v0, v2, vcc
	v_max_i32_e32 v245, 0, v233
	v_lshl_add_u32 v245, v245, 9, v89
	v_cmp_lt_i32_e64 s[98:99], -1, v230
	v_cmp_lt_i32_e64 s[100:101], -1, v231
	v_cmp_lt_i32_e64 s[38:39], -1, v232
	v_cndmask_b32_e64 v242, v246, v242, s[98:99]
	v_cmp_lt_i32_e64 s[98:99], -1, v233
	v_cndmask_b32_e64 v243, v246, v243, s[100:101]
	v_cndmask_b32_e64 v244, v246, v244, s[38:39]
	s_nop 0
	v_cndmask_b32_e64 v245, v246, v245, s[98:99]
	v_lshl_add_u32 v234, v230, 9, v89
	v_lshl_add_u32 v235, v231, 9, v89
	v_lshl_add_u32 v236, v232, 9, v89
	v_lshl_add_u32 v237, v233, 9, v89
	v_mov_b32_e32 v238, 0x400
	v_mov_b32_e32 v239, 0xfffffc00
	v_cndmask_b32_e64 v238, v238, v239, vcc
.LBB0_733:
	ds_read_b128 v[214:217], v242 offset:4096
	ds_read_b128 v[218:221], v243 offset:4096
	ds_read_b128 v[222:225], v244 offset:4096
	ds_read_b128 v[226:229], v245 offset:4096
	ds_read_b128 v[84:87], v3
	v_add_u32_e32 v0, 2, v0
	v_add_u32_e32 v2, -2, v2
	v_add_u32_e32 v3, 64, v3
	v_add_u32_e32 v234, v238, v234
	v_add_u32_e32 v235, v238, v235
	v_add_u32_e32 v236, v238, v236
	v_add_u32_e32 v237, v238, v237
	v_cmp_lt_i32_e64 s[98:99], v234, v89
	v_cmp_lt_i32_e64 s[100:101], v235, v89
	v_cmp_lt_i32_e64 s[38:39], v236, v89
	v_cndmask_b32_e64 v242, v234, v246, s[98:99]
	v_cmp_lt_i32_e64 s[98:99], v237, v89
	v_cndmask_b32_e64 v243, v235, v246, s[100:101]
	v_cndmask_b32_e64 v244, v236, v246, s[38:39]
	s_nop 0
	v_cndmask_b32_e64 v245, v237, v246, s[98:99]
	s_add_i32 s43, s43, 1
	s_cmp_lt_i32 s43, s42
	s_waitcnt lgkmcnt(0)
	v_mfma_f32_16x16x32_bf16 v[80:83], v[214:217], v[84:87], v[80:83]
	v_mfma_f32_16x16x32_bf16 v[76:79], v[218:221], v[84:87], v[76:79]
	v_mfma_f32_16x16x32_bf16 v[72:75], v[222:225], v[84:87], v[72:75]
	v_mfma_f32_16x16x32_bf16 v[68:71], v[226:229], v[84:87], v[68:71]
	s_cbranch_scc1 .LBB0_733
	s_branch .LBB0_735

.LBB0_735:
	s_max_i32 s2, s2, 16
	s_and_b64 s[0:1], vcc, exec
	s_cselect_b32 s0, 16, s2
	s_min_i32 s1, s3, 31
	s_and_b64 s[2:3], vcc, exec
	s_cselect_b32 s2, s1, 31
	s_cmp_gt_i32 s0, s2
	s_barrier
	s_waitcnt vmcnt(3)
	ds_write_b128 v94, v[52:55] offset:36864
	s_waitcnt vmcnt(2)
	ds_write_b128 v94, v[56:59] offset:41088
	s_waitcnt vmcnt(1)
	ds_write_b128 v94, v[60:63] offset:45312
	s_waitcnt vmcnt(0)
	ds_write_b128 v94, v[64:67] offset:49536
	s_waitcnt lgkmcnt(0)
	s_barrier
	s_cbranch_scc1 .LBB0_738
	s_lshl_b32 s1, s0, 1
	s_add_i32 s3, s0, -1
	v_or_b32_e32 v0, s1, v101
	s_lshl_b32 s0, s0, 6
	v_sub_u32_e32 v0, v0, v88
	v_add3_u32 v3, v91, s0, v99
	v_readlane_b32 s0, v253, 42
	v_add_u32_e32 v0, -12, v0
	v_subrev_u32_e32 v2, s1, v92
	v_add3_u32 v3, v3, v97, s0
	v_add_u32_e32 v234, 12, v0
	v_cndmask_b32_e64 v230, v234, v2, vcc
	v_max_i32_e32 v242, 0, v230
	v_lshl_add_u32 v242, v242, 9, v89
	v_add_u32_e32 v235, 8, v0
	v_add_u32_e32 v239, 4, v2
	v_cndmask_b32_e64 v231, v235, v239, vcc
	v_max_i32_e32 v243, 0, v231
	v_lshl_add_u32 v243, v243, 9, v89
	v_add_u32_e32 v236, 4, v0
	v_add_u32_e32 v240, 8, v2
	v_cndmask_b32_e64 v232, v236, v240, vcc
	v_max_i32_e32 v244, 0, v232
	v_lshl_add_u32 v244, v244, 9, v89
	v_add_u32_e32 v241, 12, v2
	v_cndmask_b32_e64 v233, v0, v241, vcc
	v_max_i32_e32 v245, 0, v233
	v_lshl_add_u32 v245, v245, 9, v89
	v_cmp_lt_i32_e64 s[98:99], -1, v230
	v_cmp_lt_i32_e64 s[100:101], -1, v231
	v_cmp_lt_i32_e64 s[38:39], -1, v232
	v_cndmask_b32_e64 v242, v246, v242, s[98:99]
	v_cmp_lt_i32_e64 s[98:99], -1, v233
	v_cndmask_b32_e64 v243, v246, v243, s[100:101]
	v_cndmask_b32_e64 v244, v246, v244, s[38:39]
	s_nop 0
	v_cndmask_b32_e64 v245, v246, v245, s[98:99]
	v_lshl_add_u32 v234, v230, 9, v89
	v_lshl_add_u32 v235, v231, 9, v89
	v_lshl_add_u32 v236, v232, 9, v89
	v_lshl_add_u32 v237, v233, 9, v89
	v_mov_b32_e32 v238, 0x400
	v_mov_b32_e32 v239, 0xfffffc00
	v_cndmask_b32_e64 v238, v238, v239, vcc
.LBB0_737:
	ds_read_b128 v[214:217], v242 offset:4096
	ds_read_b128 v[218:221], v243 offset:4096
	ds_read_b128 v[222:225], v244 offset:4096
	ds_read_b128 v[226:229], v245 offset:4096
	ds_read_b128 v[52:55], v3
	v_add_u32_e32 v0, 2, v0
	v_add_u32_e32 v2, -2, v2
	v_add_u32_e32 v3, 64, v3
	v_add_u32_e32 v234, v238, v234
	v_add_u32_e32 v235, v238, v235
	v_add_u32_e32 v236, v238, v236
	v_add_u32_e32 v237, v238, v237
	v_cmp_lt_i32_e64 s[98:99], v234, v89
	v_cmp_lt_i32_e64 s[100:101], v235, v89
	v_cmp_lt_i32_e64 s[38:39], v236, v89
	v_cndmask_b32_e64 v242, v234, v246, s[98:99]
	v_cmp_lt_i32_e64 s[98:99], v237, v89
	v_cndmask_b32_e64 v243, v235, v246, s[100:101]
	v_cndmask_b32_e64 v244, v236, v246, s[38:39]
	s_nop 0
	v_cndmask_b32_e64 v245, v237, v246, s[98:99]
	s_add_i32 s3, s3, 1
	s_cmp_lt_i32 s3, s2
	s_waitcnt lgkmcnt(0)
	v_mfma_f32_16x16x32_bf16 v[16:19], v[214:217], v[52:55], v[16:19]
	v_mfma_f32_16x16x32_bf16 v[12:15], v[218:221], v[52:55], v[12:15]
	v_mfma_f32_16x16x32_bf16 v[8:11], v[222:225], v[52:55], v[8:11]
	v_mfma_f32_16x16x32_bf16 v[4:7], v[226:229], v[52:55], v[4:7]
	s_cbranch_scc1 .LBB0_737
.LBB0_738:
	s_max_i32 s2, s19, 16
	s_and_b64 s[0:1], vcc, exec
	s_cselect_b32 s0, 16, s2
	s_min_i32 s1, s33, 31
	s_and_b64 s[2:3], vcc, exec
	s_cselect_b32 s2, s1, 31
	s_cmp_gt_i32 s0, s2
	s_cbranch_scc1 .LBB0_741
	s_lshl_b32 s1, s0, 1
	s_add_i32 s3, s0, -1
	v_or_b32_e32 v0, s1, v101
	s_lshl_b32 s0, s0, 6
	v_sub_u32_e32 v0, v0, v88
	v_subrev_u32_e32 v2, s1, v92
	v_add3_u32 v3, v91, s0, v99
	v_readlane_b32 s0, v253, 42
	v_subrev_u32_e32 v0, 28, v0
	v_add_u32_e32 v2, 28, v2
	v_add3_u32 v3, v3, v97, s0
	v_add_u32_e32 v234, 12, v0
	v_add_u32_e32 v238, -12, v2
	v_cndmask_b32_e64 v230, v234, v238, vcc
	v_max_i32_e32 v242, 0, v230
	v_lshl_add_u32 v242, v242, 9, v89
	v_add_u32_e32 v235, 8, v0
	v_add_u32_e32 v239, -8, v2
	v_cndmask_b32_e64 v231, v235, v239, vcc
	v_max_i32_e32 v243, 0, v231
	v_lshl_add_u32 v243, v243, 9, v89
	v_add_u32_e32 v236, 4, v0
	v_add_u32_e32 v240, -4, v2
	v_cndmask_b32_e64 v232, v236, v240, vcc
	v_max_i32_e32 v244, 0, v232
	v_lshl_add_u32 v244, v244, 9, v89
	v_cndmask_b32_e64 v233, v0, v2, vcc
	v_max_i32_e32 v245, 0, v233
	v_lshl_add_u32 v245, v245, 9, v89
	v_cmp_lt_i32_e64 s[98:99], -1, v230
	v_cmp_lt_i32_e64 s[100:101], -1, v231
	v_cmp_lt_i32_e64 s[38:39], -1, v232
	v_cndmask_b32_e64 v242, v246, v242, s[98:99]
	v_cmp_lt_i32_e64 s[98:99], -1, v233
	v_cndmask_b32_e64 v243, v246, v243, s[100:101]
	v_cndmask_b32_e64 v244, v246, v244, s[38:39]
	s_nop 0
	v_cndmask_b32_e64 v245, v246, v245, s[98:99]
	v_lshl_add_u32 v234, v230, 9, v89
	v_lshl_add_u32 v235, v231, 9, v89
	v_lshl_add_u32 v236, v232, 9, v89
	v_lshl_add_u32 v237, v233, 9, v89
	v_mov_b32_e32 v238, 0x400
	v_mov_b32_e32 v239, 0xfffffc00
	v_cndmask_b32_e64 v238, v238, v239, vcc
.LBB0_740:
	ds_read_b128 v[214:217], v242 offset:4096
	ds_read_b128 v[218:221], v243 offset:4096
	ds_read_b128 v[222:225], v244 offset:4096
	ds_read_b128 v[226:229], v245 offset:4096
	ds_read_b128 v[52:55], v3
	v_add_u32_e32 v0, 2, v0
	v_add_u32_e32 v2, -2, v2
	v_add_u32_e32 v3, 64, v3
	v_add_u32_e32 v234, v238, v234
	v_add_u32_e32 v235, v238, v235
	v_add_u32_e32 v236, v238, v236
	v_add_u32_e32 v237, v238, v237
	v_cmp_lt_i32_e64 s[98:99], v234, v89
	v_cmp_lt_i32_e64 s[100:101], v235, v89
	v_cmp_lt_i32_e64 s[38:39], v236, v89
	v_cndmask_b32_e64 v242, v234, v246, s[98:99]
	v_cmp_lt_i32_e64 s[98:99], v237, v89
	v_cndmask_b32_e64 v243, v235, v246, s[100:101]
	v_cndmask_b32_e64 v244, v236, v246, s[38:39]
	s_nop 0
	v_cndmask_b32_e64 v245, v237, v246, s[98:99]
	s_add_i32 s3, s3, 1
	s_cmp_lt_i32 s3, s2
	s_waitcnt lgkmcnt(0)
	v_mfma_f32_16x16x32_bf16 v[32:35], v[214:217], v[52:55], v[32:35]
	v_mfma_f32_16x16x32_bf16 v[28:31], v[218:221], v[52:55], v[28:31]
	v_mfma_f32_16x16x32_bf16 v[24:27], v[222:225], v[52:55], v[24:27]
	v_mfma_f32_16x16x32_bf16 v[20:23], v[226:229], v[52:55], v[20:23]
	s_cbranch_scc1 .LBB0_740
.LBB0_741:
	s_max_i32 s2, s36, 16
	s_and_b64 s[0:1], vcc, exec
	s_cselect_b32 s0, 16, s2
	s_min_i32 s1, s37, 31
	s_and_b64 s[2:3], vcc, exec
	s_cselect_b32 s2, s1, 31
	s_cmp_gt_i32 s0, s2
	s_cbranch_scc1 .LBB0_744
	s_lshl_b32 s1, s0, 1
	s_add_i32 s3, s0, -1
	v_or_b32_e32 v0, s1, v101
	s_lshl_b32 s0, s0, 6
	v_sub_u32_e32 v0, v0, v88
	v_subrev_u32_e32 v2, s1, v92
	v_add3_u32 v3, v91, s0, v99
	v_readlane_b32 s0, v253, 42
	v_subrev_u32_e32 v0, 44, v0
	v_add_u32_e32 v2, 44, v2
	v_add3_u32 v3, v3, v97, s0
	v_add_u32_e32 v234, 12, v0
	v_add_u32_e32 v238, -12, v2
	v_cndmask_b32_e64 v230, v234, v238, vcc
	v_max_i32_e32 v242, 0, v230
	v_lshl_add_u32 v242, v242, 9, v89
	v_add_u32_e32 v235, 8, v0
	v_add_u32_e32 v239, -8, v2
	v_cndmask_b32_e64 v231, v235, v239, vcc
	v_max_i32_e32 v243, 0, v231
	v_lshl_add_u32 v243, v243, 9, v89
	v_add_u32_e32 v236, 4, v0
	v_add_u32_e32 v240, -4, v2
	v_cndmask_b32_e64 v232, v236, v240, vcc
	v_max_i32_e32 v244, 0, v232
	v_lshl_add_u32 v244, v244, 9, v89
	v_cndmask_b32_e64 v233, v0, v2, vcc
	v_max_i32_e32 v245, 0, v233
	v_lshl_add_u32 v245, v245, 9, v89
	v_cmp_lt_i32_e64 s[98:99], -1, v230
	v_cmp_lt_i32_e64 s[100:101], -1, v231
	v_cmp_lt_i32_e64 s[38:39], -1, v232
	v_cndmask_b32_e64 v242, v246, v242, s[98:99]
	v_cmp_lt_i32_e64 s[98:99], -1, v233
	v_cndmask_b32_e64 v243, v246, v243, s[100:101]
	v_cndmask_b32_e64 v244, v246, v244, s[38:39]
	s_nop 0
	v_cndmask_b32_e64 v245, v246, v245, s[98:99]
	v_lshl_add_u32 v234, v230, 9, v89
	v_lshl_add_u32 v235, v231, 9, v89
	v_lshl_add_u32 v236, v232, 9, v89
	v_lshl_add_u32 v237, v233, 9, v89
	v_mov_b32_e32 v238, 0x400
	v_mov_b32_e32 v239, 0xfffffc00
	v_cndmask_b32_e64 v238, v238, v239, vcc
.LBB0_743:
	ds_read_b128 v[214:217], v242 offset:4096
	ds_read_b128 v[218:221], v243 offset:4096
	ds_read_b128 v[222:225], v244 offset:4096
	ds_read_b128 v[226:229], v245 offset:4096
	ds_read_b128 v[52:55], v3
	v_add_u32_e32 v0, 2, v0
	v_add_u32_e32 v2, -2, v2
	v_add_u32_e32 v3, 64, v3
	v_add_u32_e32 v234, v238, v234
	v_add_u32_e32 v235, v238, v235
	v_add_u32_e32 v236, v238, v236
	v_add_u32_e32 v237, v238, v237
	v_cmp_lt_i32_e64 s[98:99], v234, v89
	v_cmp_lt_i32_e64 s[100:101], v235, v89
	v_cmp_lt_i32_e64 s[38:39], v236, v89
	v_cndmask_b32_e64 v242, v234, v246, s[98:99]
	v_cmp_lt_i32_e64 s[98:99], v237, v89
	v_cndmask_b32_e64 v243, v235, v246, s[100:101]
	v_cndmask_b32_e64 v244, v236, v246, s[38:39]
	s_nop 0
	v_cndmask_b32_e64 v245, v237, v246, s[98:99]
	s_add_i32 s3, s3, 1
	s_cmp_lt_i32 s3, s2
	s_waitcnt lgkmcnt(0)
	v_mfma_f32_16x16x32_bf16 v[48:51], v[214:217], v[52:55], v[48:51]
	v_mfma_f32_16x16x32_bf16 v[44:47], v[218:221], v[52:55], v[44:47]
	v_mfma_f32_16x16x32_bf16 v[40:43], v[222:225], v[52:55], v[40:43]
	v_mfma_f32_16x16x32_bf16 v[36:39], v[226:229], v[52:55], v[36:39]
	s_cbranch_scc1 .LBB0_743
.LBB0_744:
	s_max_i32 s2, s40, 16
	s_and_b64 s[0:1], vcc, exec
	s_cselect_b32 s0, 16, s2
	s_min_i32 s1, s41, 31
	s_and_b64 s[2:3], vcc, exec
	s_cselect_b32 s2, s1, 31
	s_mov_b64 s[38:39], -1
	s_cmp_le_i32 s0, s2
	v_add_u32_e32 v0, 48, v88
	v_add_u32_e32 v2, 52, v88
	v_add_u32_e32 v3, 56, v88
	v_add_u32_e32 v102, 60, v88
	s_cbranch_scc0 .LBB0_748
	s_lshl_b32 s1, s0, 1
	v_or_b32_e32 v52, s1, v101
	v_add_u32_e32 v92, 60, v88
	v_sub_u32_e32 v52, v52, v88
	s_add_i32 s3, s0, -1
	v_subrev_u32_e32 v103, 60, v52
	v_sub_u32_e32 v52, v92, v101
	s_lshl_b32 s0, s0, 6
	v_subrev_u32_e32 v101, s1, v52
	v_add3_u32 v52, v91, s0, v99
	v_readlane_b32 s0, v253, 42
	v_mov_b64_e32 v[56:57], v[72:73]
	v_mov_b64_e32 v[60:61], v[76:77]
	v_add3_u32 v91, v52, v97, s0
	v_mov_b64_e32 v[52:53], v[68:69]
	v_mov_b64_e32 v[64:65], v[80:81]
	v_add_u32_e32 v98, 48, v88
	v_add_u32_e32 v96, 52, v88
	v_add_u32_e32 v94, 56, v88
	v_mov_b64_e32 v[54:55], v[70:71]
	v_mov_b64_e32 v[58:59], v[74:75]
	v_mov_b64_e32 v[62:63], v[78:79]
	v_mov_b64_e32 v[66:67], v[82:83]
	v_add_u32_e32 v234, 12, v103
	v_add_u32_e32 v238, -12, v101
	v_cndmask_b32_e64 v230, v234, v238, vcc
	v_max_i32_e32 v242, 0, v230
	v_lshl_add_u32 v242, v242, 9, v89
	v_add_u32_e32 v235, 8, v103
	v_add_u32_e32 v239, -8, v101
	v_cndmask_b32_e64 v231, v235, v239, vcc
	v_max_i32_e32 v243, 0, v231
	v_lshl_add_u32 v243, v243, 9, v89
	v_add_u32_e32 v236, 4, v103
	v_add_u32_e32 v240, -4, v101
	v_cndmask_b32_e64 v232, v236, v240, vcc
	v_max_i32_e32 v244, 0, v232
	v_lshl_add_u32 v244, v244, 9, v89
	v_cndmask_b32_e64 v233, v103, v101, vcc
	v_max_i32_e32 v245, 0, v233
	v_lshl_add_u32 v245, v245, 9, v89
	v_cmp_lt_i32_e64 s[98:99], -1, v230
	v_cmp_lt_i32_e64 s[100:101], -1, v231
	v_cmp_lt_i32_e64 s[38:39], -1, v232
	v_cndmask_b32_e64 v242, v246, v242, s[98:99]
	v_cmp_lt_i32_e64 s[98:99], -1, v233
	v_cndmask_b32_e64 v243, v246, v243, s[100:101]
	v_cndmask_b32_e64 v244, v246, v244, s[38:39]
	s_nop 0
	v_cndmask_b32_e64 v245, v246, v245, s[98:99]
	v_lshl_add_u32 v234, v230, 9, v89
	v_lshl_add_u32 v235, v231, 9, v89
	v_lshl_add_u32 v236, v232, 9, v89
	v_lshl_add_u32 v237, v233, 9, v89
	v_mov_b32_e32 v238, 0x400
	v_mov_b32_e32 v239, 0xfffffc00
	v_cndmask_b32_e64 v238, v238, v239, vcc
.LBB0_746:
	ds_read_b128 v[214:217], v242 offset:4096
	ds_read_b128 v[218:221], v243 offset:4096
	ds_read_b128 v[222:225], v244 offset:4096
	ds_read_b128 v[226:229], v245 offset:4096
	ds_read_b128 v[84:87], v91
	v_add_u32_e32 v103, 2, v103
	v_add_u32_e32 v101, -2, v101
	v_add_u32_e32 v91, 64, v91
	v_add_u32_e32 v234, v238, v234
	v_add_u32_e32 v235, v238, v235
	v_add_u32_e32 v236, v238, v236
	v_add_u32_e32 v237, v238, v237
	v_cmp_lt_i32_e64 s[98:99], v234, v89
	v_cmp_lt_i32_e64 s[100:101], v235, v89
	v_cmp_lt_i32_e64 s[38:39], v236, v89
	v_cndmask_b32_e64 v242, v234, v246, s[98:99]
	v_cmp_lt_i32_e64 s[98:99], v237, v89
	v_cndmask_b32_e64 v243, v235, v246, s[100:101]
	v_cndmask_b32_e64 v244, v236, v246, s[38:39]
	s_nop 0
	v_cndmask_b32_e64 v245, v237, v246, s[98:99]
	s_add_i32 s3, s3, 1
	s_cmp_lt_i32 s3, s2
	s_waitcnt lgkmcnt(0)
	v_mfma_f32_16x16x32_bf16 v[64:67], v[214:217], v[84:87], v[64:67]
	v_mfma_f32_16x16x32_bf16 v[60:63], v[218:221], v[84:87], v[60:63]
	v_mfma_f32_16x16x32_bf16 v[56:59], v[222:225], v[84:87], v[56:59]
	v_mfma_f32_16x16x32_bf16 v[52:55], v[226:229], v[84:87], v[52:55]
	s_cbranch_scc1 .LBB0_746
	s_mov_b64 s[38:39], 0
